# scan: conv-stage parameter loads issued together with the raw tile loads (one more memory round trip per item removed)
# baseline (speedup 1.0000x reference)
; __device__ __forceinline__ int tid_opaque(int wv) { return wv * 64 + lane_fresh(); }
; __device__ __forceinline__ void scan_mfma(PP p, unsigned char* shm, int wv) {
;     ...
;         const int id = item < 512 ? item : 512 + ((item - 512) >> 2);
;         const int quarter = item < 512 ? -1 : ((item - 512) & 3);
;         int rowbase, t0, seqlen; bool latent;
;         if (id < 512) { const int b = id >> 8, k = id & 255; t0 = 64 * k; rowbase = b * S + t0; seqlen = S; latent = true; }
;         else { const int j = id - 512, b = j >> 2, k = j & 3; t0 = 64 * k; rowbase = NLAT + b * LC + t0; seqlen = LC; latent = false; }
;         const int seqbase = rowbase - t0;
;         ScanW w0, w1;
;         if (quarter < 0) scan_loadw(p, 0, n, 0, l31, hl, w0);
;         {
;             const int tid = tid_opaque(wv);
;             bf16_t* raw = (bf16_t*)(shm + 66560);
; #pragma unroll
;             for (int i = 0; i < 9; ++i) {
;                 const int piece = tid + 512 * i;
;                 if (piece < 67 * 64) {
;                     const int row = piece >> 6, c8 = piece & 63, tt = t0 - 2 + row;
;                     u32x4 v = {0u, 0u, 0u, 0u};
;                     if (tt >= 0 && tt < seqlen) v = *(const u32x4*)(proj + (size_t)(seqbase + tt) * DIN + 8 * c8);
;                     *(u32x4*)(raw + row * 512 + 8 * c8) = v;
;                 }
;             }
;             __syncthreads();
;             const int cq = tid & 127, tq = tid >> 7, c4 = 4 * cq;
;             const f32x4 k0 = *(const f32x4*)(p->rnn_conv_w + c4), k1 = *(const f32x4*)(p->rnn_conv_w + 512 + c4), k2 = *(const f32x4*)(p->rnn_conv_w + 1024 + c4),
;                         k3 = *(const f32x4*)(p->rnn_conv_w + 1536 + c4), kb = *(const f32x4*)(p->rnn_conv_b + c4);
.LBB0_332:
	s_add_i32 s4, s78, 0xfffffe00
	s_lshr_b32 s5, s4, 2
	s_addk_i32 s5, 0x200
	s_lshl_b32 s4, s78, 6
	s_lshl_b32 s35, s5, 6
	s_and_b32 s34, s4, 0x3fc0
	s_and_b32 s36, s35, 0xc0
	s_and_b64 s[30:31], s[22:23], exec
	s_mov_b32 s30, -1
	s_cselect_b32 s38, s34, s36
	v_mbcnt_lo_u32_b32 v0, s30, 0
	v_mbcnt_hi_u32_b32 v0, s30, v0
	v_add_u32_e32 v54, s33, v0
	v_lshlrev_b32_e32 v0, 4, v0
	s_cselect_b32 s4, s4, s35
	v_and_b32_e32 v0, 0x3f0, v0
	s_cselect_b32 s37, 0x4000, s64
	s_sub_i32 s36, s4, s38
	s_add_i32 s38, s38, -2
	v_lshl_add_u64 v[38:39], s[10:11], 0, v[0:1]
	v_add_u32_e32 v0, s65, v0
	s_mov_b64 s[30:31], exec
	v_ashrrev_i32_e32 v95, 6, v54
	v_add_u32_e32 v96, s38, v95
	v_lshl_add_u32 v86, v95, 10, v0
	v_mov_b32_e32 v2, 0
	v_mov_b32_e32 v3, 0
	v_mov_b32_e32 v4, 0
	v_mov_b32_e32 v5, 0
	v_cmp_gt_u32_e32 vcc, s37, v96
	v_cmp_gt_i32_e64 s[34:35], s66, v54
	s_and_b64 vcc, vcc, s[34:35]
	s_and_b64 exec, s[30:31], vcc
	v_add_u32_e32 v97, s36, v96
	v_mad_i64_i32 v[98:99], s[40:41], v97, s67, v[38:39]
	global_load_dwordx4 v[2:5], v[98:99], off
	s_mov_b64 exec, s[30:31]
	v_add_u32_e32 v95, 0x200, v54
	v_ashrrev_i32_e32 v95, 6, v95
	v_add_u32_e32 v96, s38, v95
	v_lshl_add_u32 v87, v95, 10, v0
	v_mov_b32_e32 v6, 0
	v_mov_b32_e32 v7, 0
	v_mov_b32_e32 v8, 0
	v_mov_b32_e32 v9, 0
	v_cmp_gt_u32_e32 vcc, s37, v96
	v_cmp_gt_i32_e64 s[34:35], s68, v54
	s_and_b64 vcc, vcc, s[34:35]
	s_and_b64 exec, s[30:31], vcc
	v_add_u32_e32 v97, s36, v96
	v_mad_i64_i32 v[98:99], s[40:41], v97, s67, v[38:39]
	global_load_dwordx4 v[6:9], v[98:99], off
	s_mov_b64 exec, s[30:31]
	v_add_u32_e32 v95, 0x400, v54
	v_ashrrev_i32_e32 v95, 6, v95
	v_add_u32_e32 v96, s38, v95
	v_lshl_add_u32 v88, v95, 10, v0
	v_mov_b32_e32 v10, 0
	v_mov_b32_e32 v11, 0
	v_mov_b32_e32 v12, 0
	v_mov_b32_e32 v13, 0
	v_cmp_gt_u32_e32 vcc, s37, v96
	v_cmp_gt_i32_e64 s[34:35], s69, v54
	s_and_b64 vcc, vcc, s[34:35]
	s_and_b64 exec, s[30:31], vcc
	v_add_u32_e32 v97, s36, v96
	v_mad_i64_i32 v[98:99], s[40:41], v97, s67, v[38:39]
	global_load_dwordx4 v[10:13], v[98:99], off
	s_mov_b64 exec, s[30:31]
	v_add_u32_e32 v95, 0x600, v54
	v_ashrrev_i32_e32 v95, 6, v95
	v_add_u32_e32 v96, s38, v95
	v_lshl_add_u32 v89, v95, 10, v0
	v_mov_b32_e32 v14, 0
	v_mov_b32_e32 v15, 0
	v_mov_b32_e32 v16, 0
	v_mov_b32_e32 v17, 0
	v_cmp_gt_u32_e32 vcc, s37, v96
	v_cmp_gt_i32_e64 s[34:35], s70, v54
	s_and_b64 vcc, vcc, s[34:35]
	s_and_b64 exec, s[30:31], vcc
	v_add_u32_e32 v97, s36, v96
	v_mad_i64_i32 v[98:99], s[40:41], v97, s67, v[38:39]
	global_load_dwordx4 v[14:17], v[98:99], off
	s_mov_b64 exec, s[30:31]
	v_add_u32_e32 v95, 0x800, v54
	v_ashrrev_i32_e32 v95, 6, v95
	v_add_u32_e32 v96, s38, v95
	v_lshl_add_u32 v90, v95, 10, v0
	v_mov_b32_e32 v18, 0
	v_mov_b32_e32 v19, 0
	v_mov_b32_e32 v20, 0
	v_mov_b32_e32 v21, 0
	v_cmp_gt_u32_e32 vcc, s37, v96
	v_cmp_gt_i32_e64 s[34:35], s71, v54
	s_and_b64 vcc, vcc, s[34:35]
	s_and_b64 exec, s[30:31], vcc
	v_add_u32_e32 v97, s36, v96
	v_mad_i64_i32 v[98:99], s[40:41], v97, s67, v[38:39]
	global_load_dwordx4 v[18:21], v[98:99], off
	s_mov_b64 exec, s[30:31]
	v_add_u32_e32 v95, 0xa00, v54
	v_ashrrev_i32_e32 v95, 6, v95
	v_add_u32_e32 v96, s38, v95
	v_lshl_add_u32 v91, v95, 10, v0
	v_mov_b32_e32 v22, 0
	v_mov_b32_e32 v23, 0
	v_mov_b32_e32 v24, 0
	v_mov_b32_e32 v25, 0
	v_cmp_gt_u32_e32 vcc, s37, v96
	v_cmp_gt_i32_e64 s[34:35], s72, v54
	s_and_b64 vcc, vcc, s[34:35]
	s_and_b64 exec, s[30:31], vcc
	v_add_u32_e32 v97, s36, v96
	v_mad_i64_i32 v[98:99], s[40:41], v97, s67, v[38:39]
	global_load_dwordx4 v[22:25], v[98:99], off
	s_mov_b64 exec, s[30:31]
	v_add_u32_e32 v95, 0xc00, v54
	v_ashrrev_i32_e32 v95, 6, v95
	v_add_u32_e32 v96, s38, v95
	v_lshl_add_u32 v92, v95, 10, v0
	v_mov_b32_e32 v26, 0
	v_mov_b32_e32 v27, 0
	v_mov_b32_e32 v28, 0
	v_mov_b32_e32 v29, 0
	v_cmp_gt_u32_e32 vcc, s37, v96
	v_cmp_gt_i32_e64 s[34:35], s73, v54
	s_and_b64 vcc, vcc, s[34:35]
	s_and_b64 exec, s[30:31], vcc
	v_add_u32_e32 v97, s36, v96
	v_mad_i64_i32 v[98:99], s[40:41], v97, s67, v[38:39]
	global_load_dwordx4 v[26:29], v[98:99], off
	s_mov_b64 exec, s[30:31]
	v_add_u32_e32 v95, 0xe00, v54
	v_ashrrev_i32_e32 v95, 6, v95
	v_add_u32_e32 v96, s38, v95
	v_lshl_add_u32 v93, v95, 10, v0
	v_mov_b32_e32 v30, 0
	v_mov_b32_e32 v31, 0
	v_mov_b32_e32 v32, 0
	v_mov_b32_e32 v33, 0
	v_cmp_gt_u32_e32 vcc, s37, v96
	v_cmp_gt_i32_e64 s[34:35], s74, v54
	s_and_b64 vcc, vcc, s[34:35]
	s_and_b64 exec, s[30:31], vcc
	v_add_u32_e32 v97, s36, v96
	v_mad_i64_i32 v[98:99], s[40:41], v97, s67, v[38:39]
	global_load_dwordx4 v[30:33], v[98:99], off
	s_mov_b64 exec, s[30:31]
	v_add_u32_e32 v95, 0x1000, v54
	v_ashrrev_i32_e32 v95, 6, v95
	v_add_u32_e32 v96, s38, v95
	v_lshl_add_u32 v94, v95, 10, v0
	v_mov_b32_e32 v82, 0
	v_mov_b32_e32 v83, 0
	v_mov_b32_e32 v84, 0
	v_mov_b32_e32 v85, 0
	v_cmp_gt_u32_e32 vcc, s37, v96
	v_cmp_gt_i32_e64 s[34:35], s61, v54
	s_and_b64 vcc, vcc, s[34:35]
	s_and_b64 exec, s[30:31], vcc
	v_add_u32_e32 v97, s36, v96
	v_mad_i64_i32 v[98:99], s[40:41], v97, s67, v[38:39]
	global_load_dwordx4 v[82:85], v[98:99], off
	s_mov_b64 exec, s[30:31]
	s_load_dwordx4 s[36:39], s[8:9], 0x40
	v_lshlrev_b32_e32 v0, 2, v54
	v_and_b32_e32 v55, 0x1fc, v0
	v_lshlrev_b32_e32 v0, 2, v55
	s_waitcnt lgkmcnt(0)
	global_load_dwordx4 v[34:37], v0, s[36:37]
	global_load_dwordx4 v[46:49], v0, s[38:39]
	v_lshl_add_u64 v[38:39], s[36:37], 0, v[0:1]
	global_load_dwordx4 v[42:45], v0, s[36:37] offset:2048
	v_add_co_u32_e32 v38, vcc, s75, v38
	v_ashrrev_i32_e32 v56, 3, v54
	s_nop 0
	v_addc_co_u32_e32 v39, vcc, 0, v39, vcc
	global_load_dwordx4 v[50:53], v[38:39], off
	s_nop 0
	global_load_dwordx4 v[38:41], v[38:39], off offset:2048
	s_waitcnt vmcnt(0)
	s_cmp_lg_u64 s[22:23], 0
	s_cbranch_scc0 .Lscan_nomul0
	v_mul_f32_e32 v194, 0x3fb8aa3b, v100

; __device__ __forceinline__ unsigned pk2(float lo, float hi) { unsigned r; asm("v_cvt_pk_bf16_f32 %0, %1, %2" : "=v"(r) : "v"(lo), "v"(hi)); return r; }
; __device__ __forceinline__ float bflo(unsigned w) { return __uint_as_float(w << 16); }
; __device__ __forceinline__ float bfhi(unsigned w) { return __uint_as_float(w & 0xFFFF0000u); }
; __device__ __forceinline__ void scan_mfma(PP p, unsigned char* shm, int wv) {
;     ...
;             const int cq = tid & 127, tq = tid >> 7, c4 = 4 * cq;
;             const f32x4 k0 = *(const f32x4*)(p->rnn_conv_w + c4), k1 = *(const f32x4*)(p->rnn_conv_w + 512 + c4), k2 = *(const f32x4*)(p->rnn_conv_w + 1024 + c4),
;                         k3 = *(const f32x4*)(p->rnn_conv_w + 1536 + c4), kb = *(const f32x4*)(p->rnn_conv_b + c4);
;             auto ld4 = [&](int row) -> f32x4 { const u32x2 w = *(const u32x2*)(raw + row * 512 + c4); f32x4 r; r[0] = bflo(w.x); r[1] = bfhi(w.x); r[2] = bflo(w.y); r[3] = bfhi(w.y); return r; };
;             f32x4 xm2 = ld4(16 * tq), xm1 = ld4(16 * tq + 1), x0 = ld4(16 * tq + 2);
; #pragma unroll
;             for (int t = 0; t < 16; ++t) {
;                 const f32x4 xp1 = ld4(16 * tq + t + 3);
;                 const f32x4 o = kb + k0 * xm2 + k1 * xm1 + k2 * x0 + k3 * xp1;
;                 u32x2 w; w.x = pk2(o[0], o[1]); w.y = pk2(o[2], o[3]);
;                 *(u32x2*)(xs + (16 * tq + t) * XS + c4) = w;
;                 xm2 = xm1; xm1 = x0; x0 = xp1;
.LBB0_368:
	s_or_b64 exec, exec, s[30:31]
	s_waitcnt lgkmcnt(0)
	s_barrier
	v_and_b32_e32 v54, -16, v56
	v_lshlrev_b32_e32 v0, 1, v55
	v_lshlrev_b32_e32 v55, 10, v54
	v_add3_u32 v57, s65, v55, v0
	ds_read2st64_b64 v[58:61], v57 offset1:2
	v_add_u32_e32 v156, s65, v0
	v_add_u32_e32 v158, v156, v55
	ds_read_b64 v[62:63], v57 offset:2048
	ds_read_b64 v[64:65], v158 offset:3072
	v_add_u32_e32 v0, 0, v0
	s_waitcnt lgkmcnt(2)
	v_lshlrev_b32_e32 v66, 16, v58
	v_and_b32_e32 v67, 0xffff0000, v58
	v_lshlrev_b32_e32 v58, 16, v59
	v_and_b32_e32 v59, 0xffff0000, v59
	v_lshlrev_b32_e32 v68, 16, v60
	v_and_b32_e32 v69, 0xffff0000, v60
	v_lshlrev_b32_e32 v60, 16, v61
	v_and_b32_e32 v61, 0xffff0000, v61
	s_waitcnt lgkmcnt(1)
	v_lshlrev_b32_e32 v70, 16, v62
	v_and_b32_e32 v71, 0xffff0000, v62
	v_lshlrev_b32_e32 v62, 16, v63
	v_and_b32_e32 v63, 0xffff0000, v63
	s_waitcnt lgkmcnt(0)
	v_lshlrev_b32_e32 v72, 16, v64
	v_and_b32_e32 v73, 0xffff0000, v64
	v_mad_u64_u32 v[54:55], s[30:31], v54, s51, v[0:1]
	v_lshlrev_b32_e32 v64, 16, v65
	v_and_b32_e32 v65, 0xffff0000, v65
	s_and_b64 s[30:31], s[22:23], exec
	s_cselect_b32 s34, s78, s5
	s_and_b32 s5, s78, 3
	s_and_b64 s[30:31], s[22:23], exec
	s_cselect_b32 s79, -1, s5
	s_ashr_i32 s5, s4, 31
	s_lshl_b64 s[4:5], s[4:5], 10
	s_mov_b32 s80, 0
	s_mov_b64 s[44:45], -1
	s_waitcnt vmcnt(3)
	v_pk_fma_f32 v[66:67], v[34:35], v[66:67], v[46:47]
	v_pk_fma_f32 v[58:59], v[36:37], v[58:59], v[48:49]
	v_pk_fma_f32 v[76:77], v[36:37], v[60:61], v[48:49]
	s_waitcnt vmcnt(2)
	v_pk_fma_f32 v[58:59], v[44:45], v[60:61], v[58:59]
	v_pk_fma_f32 v[60:61], v[42:43], v[68:69], v[66:67]
	v_pk_fma_f32 v[74:75], v[34:35], v[68:69], v[46:47]
	v_pk_fma_f32 v[78:79], v[36:37], v[62:63], v[48:49]
	s_waitcnt vmcnt(1)
	v_pk_fma_f32 v[60:61], v[50:51], v[70:71], v[60:61]
	v_pk_fma_f32 v[58:59], v[52:53], v[62:63], v[58:59]
	s_waitcnt vmcnt(0)
	v_pk_fma_f32 v[60:61], v[38:39], v[72:73], v[60:61]
	v_pk_fma_f32 v[58:59], v[40:41], v[64:65], v[58:59]
	v_cvt_pk_bf16_f32 v60, v60, v61
	v_pk_fma_f32 v[66:67], v[44:45], v[62:63], v[76:77]
	v_cvt_pk_bf16_f32 v61, v58, v59
	ds_write_b64 v54, v[60:61]
	ds_read_b64 v[58:59], v158 offset:4096
	v_pk_fma_f32 v[68:69], v[42:43], v[70:71], v[74:75]
	v_pk_fma_f32 v[146:147], v[36:37], v[64:65], v[48:49]
	v_pk_fma_f32 v[62:63], v[44:45], v[64:65], v[78:79]
	v_pk_fma_f32 v[68:69], v[50:51], v[72:73], v[68:69]
	v_pk_fma_f32 v[64:65], v[52:53], v[64:65], v[66:67]
	s_waitcnt lgkmcnt(0)
	v_lshlrev_b32_e32 v66, 16, v58
	v_and_b32_e32 v67, 0xffff0000, v58
	v_lshlrev_b32_e32 v58, 16, v59
	v_and_b32_e32 v59, 0xffff0000, v59
	v_pk_fma_f32 v[68:69], v[38:39], v[66:67], v[68:69]
	v_pk_fma_f32 v[64:65], v[40:41], v[58:59], v[64:65]
	v_cvt_pk_bf16_f32 v68, v68, v69
	v_pk_fma_f32 v[80:81], v[34:35], v[70:71], v[46:47]
	v_cvt_pk_bf16_f32 v69, v64, v65
	ds_write_b64 v54, v[68:69] offset:1040
	ds_read_b64 v[64:65], v158 offset:5120
	v_pk_fma_f32 v[60:61], v[42:43], v[72:73], v[80:81]
	v_pk_fma_f32 v[154:155], v[34:35], v[72:73], v[46:47]
	v_pk_fma_f32 v[60:61], v[50:51], v[66:67], v[60:61]
	v_pk_fma_f32 v[62:63], v[52:53], v[58:59], v[62:63]
	s_waitcnt lgkmcnt(0)
	v_lshlrev_b32_e32 v72, 16, v64
	v_and_b32_e32 v73, 0xffff0000, v64
	v_lshlrev_b32_e32 v64, 16, v65
	v_and_b32_e32 v65, 0xffff0000, v65
	v_pk_fma_f32 v[60:61], v[38:39], v[72:73], v[60:61]
	v_pk_fma_f32 v[62:63], v[40:41], v[64:65], v[62:63]
	v_cvt_pk_bf16_f32 v60, v60, v61
	v_pk_fma_f32 v[68:69], v[44:45], v[58:59], v[146:147]
	v_cvt_pk_bf16_f32 v61, v62, v63
	ds_write_b64 v54, v[60:61] offset:2080
	ds_read_b64 v[60:61], v158 offset:6144
	v_pk_fma_f32 v[70:71], v[42:43], v[66:67], v[154:155]
	v_pk_fma_f32 v[62:63], v[52:53], v[64:65], v[68:69]
	v_pk_fma_f32 v[68:69], v[50:51], v[72:73], v[70:71]
	v_pk_fma_f32 v[66:67], v[34:35], v[66:67], v[46:47]
	s_waitcnt lgkmcnt(0)
	v_lshlrev_b32_e32 v70, 16, v60
	v_and_b32_e32 v71, 0xffff0000, v60
	v_lshlrev_b32_e32 v60, 16, v61
	v_and_b32_e32 v61, 0xffff0000, v61
	v_pk_fma_f32 v[68:69], v[38:39], v[70:71], v[68:69]
	v_pk_fma_f32 v[62:63], v[40:41], v[60:61], v[62:63]
	v_cvt_pk_bf16_f32 v68, v68, v69
	v_pk_fma_f32 v[58:59], v[36:37], v[58:59], v[48:49]
	v_cvt_pk_bf16_f32 v69, v62, v63
	ds_write_b64 v54, v[68:69] offset:3120
	ds_read_b64 v[62:63], v158 offset:7168
	v_pk_fma_f32 v[66:67], v[42:43], v[72:73], v[66:67]
	v_pk_fma_f32 v[58:59], v[44:45], v[64:65], v[58:59]
	v_pk_fma_f32 v[68:69], v[34:35], v[72:73], v[46:47]
	v_pk_fma_f32 v[66:67], v[50:51], v[70:71], v[66:67]
	s_waitcnt lgkmcnt(0)
	v_lshlrev_b32_e32 v72, 16, v62
	v_and_b32_e32 v73, 0xffff0000, v62
	v_pk_fma_f32 v[58:59], v[52:53], v[60:61], v[58:59]
	v_lshlrev_b32_e32 v62, 16, v63
	v_and_b32_e32 v63, 0xffff0000, v63
	v_pk_fma_f32 v[66:67], v[38:39], v[72:73], v[66:67]
	v_pk_fma_f32 v[58:59], v[40:41], v[62:63], v[58:59]
	v_cvt_pk_bf16_f32 v66, v66, v67
	v_pk_fma_f32 v[64:65], v[36:37], v[64:65], v[48:49]
	v_cvt_pk_bf16_f32 v67, v58, v59
	ds_write_b64 v54, v[66:67] offset:4160
	ds_read_b64 v[58:59], v158 offset:8192
	v_pk_fma_f32 v[66:67], v[42:43], v[70:71], v[68:69]
	v_pk_fma_f32 v[64:65], v[44:45], v[60:61], v[64:65]
	v_pk_fma_f32 v[66:67], v[50:51], v[72:73], v[66:67]
	v_pk_fma_f32 v[64:65], v[52:53], v[62:63], v[64:65]
	s_waitcnt lgkmcnt(0)
	v_lshlrev_b32_e32 v68, 16, v58
	v_and_b32_e32 v69, 0xffff0000, v58
	v_lshlrev_b32_e32 v58, 16, v59
	v_and_b32_e32 v59, 0xffff0000, v59
	v_pk_fma_f32 v[66:67], v[38:39], v[68:69], v[66:67]
	v_pk_fma_f32 v[64:65], v[40:41], v[58:59], v[64:65]
	v_cvt_pk_bf16_f32 v66, v66, v67
	v_pk_fma_f32 v[70:71], v[34:35], v[70:71], v[46:47]
	v_cvt_pk_bf16_f32 v67, v64, v65
	ds_write_b64 v54, v[66:67] offset:5200
	ds_read_b64 v[64:65], v158 offset:9216
	v_pk_fma_f32 v[60:61], v[36:37], v[60:61], v[48:49]
	v_pk_fma_f32 v[70:71], v[42:43], v[72:73], v[70:71]
	v_pk_fma_f32 v[60:61], v[44:45], v[62:63], v[60:61]
	v_pk_fma_f32 v[70:71], v[50:51], v[68:69], v[70:71]
	s_waitcnt lgkmcnt(0)
; __device__ __forceinline__ unsigned pk2(float lo, float hi) { unsigned r; asm("v_cvt_pk_bf16_f32 %0, %1, %2" : "=v"(r) : "v"(lo), "v"(hi)); return r; }
; __device__ __forceinline__ void scan_mfma(PP p, unsigned char* shm, int wv) {
;     ...
; #pragma unroll
;             for (int t = 0; t < 16; ++t) {
;                 const f32x4 xp1 = ld4(16 * tq + t + 3);
;                 const f32x4 o = kb + k0 * xm2 + k1 * xm1 + k2 * x0 + k3 * xp1;
;                 u32x2 w; w.x = pk2(o[0], o[1]); w.y = pk2(o[2], o[3]);
;                 *(u32x2*)(xs + (16 * tq + t) * XS + c4) = w;
;                 xm2 = xm1; xm1 = x0; x0 = xp1;
	v_lshlrev_b32_e32 v66, 16, v64
	v_and_b32_e32 v67, 0xffff0000, v64
	v_lshlrev_b32_e32 v64, 16, v65
	v_and_b32_e32 v65, 0xffff0000, v65
	v_pk_fma_f32 v[60:61], v[52:53], v[58:59], v[60:61]
	v_pk_fma_f32 v[70:71], v[38:39], v[66:67], v[70:71]
	v_pk_fma_f32 v[60:61], v[40:41], v[64:65], v[60:61]
	v_cvt_pk_bf16_f32 v70, v70, v71
	v_pk_fma_f32 v[72:73], v[34:35], v[72:73], v[46:47]
	v_cvt_pk_bf16_f32 v71, v60, v61
	ds_write_b64 v54, v[70:71] offset:6240
	ds_read_b64 v[60:61], v158 offset:10240
	v_pk_fma_f32 v[62:63], v[36:37], v[62:63], v[48:49]
	v_pk_fma_f32 v[72:73], v[42:43], v[68:69], v[72:73]
	v_pk_fma_f32 v[62:63], v[44:45], v[58:59], v[62:63]
	v_pk_fma_f32 v[72:73], v[50:51], v[66:67], v[72:73]
	s_waitcnt lgkmcnt(0)
	v_lshlrev_b32_e32 v70, 16, v60
	v_and_b32_e32 v71, 0xffff0000, v60
	v_lshlrev_b32_e32 v60, 16, v61
	v_and_b32_e32 v61, 0xffff0000, v61
	v_pk_fma_f32 v[62:63], v[52:53], v[64:65], v[62:63]
	v_pk_fma_f32 v[72:73], v[38:39], v[70:71], v[72:73]
	v_pk_fma_f32 v[62:63], v[40:41], v[60:61], v[62:63]
	v_cvt_pk_bf16_f32 v72, v72, v73
	v_pk_fma_f32 v[68:69], v[34:35], v[68:69], v[46:47]
	v_cvt_pk_bf16_f32 v73, v62, v63
	ds_write_b64 v54, v[72:73] offset:7280
	ds_read_b64 v[62:63], v158 offset:11264
	v_pk_fma_f32 v[58:59], v[36:37], v[58:59], v[48:49]
	v_pk_fma_f32 v[68:69], v[42:43], v[66:67], v[68:69]
	v_pk_fma_f32 v[58:59], v[44:45], v[64:65], v[58:59]
	v_pk_fma_f32 v[68:69], v[50:51], v[70:71], v[68:69]
	s_waitcnt lgkmcnt(0)
	v_lshlrev_b32_e32 v72, 16, v62
	v_and_b32_e32 v73, 0xffff0000, v62
	v_lshlrev_b32_e32 v62, 16, v63
	v_and_b32_e32 v63, 0xffff0000, v63
	v_pk_fma_f32 v[58:59], v[52:53], v[60:61], v[58:59]
	v_pk_fma_f32 v[68:69], v[38:39], v[72:73], v[68:69]
	v_pk_fma_f32 v[58:59], v[40:41], v[62:63], v[58:59]
	v_cvt_pk_bf16_f32 v68, v68, v69
	v_pk_fma_f32 v[66:67], v[34:35], v[66:67], v[46:47]
	v_cvt_pk_bf16_f32 v69, v58, v59
	ds_write_b64 v54, v[68:69] offset:8320
	ds_read_b64 v[58:59], v158 offset:12288
	v_pk_fma_f32 v[64:65], v[36:37], v[64:65], v[48:49]
	v_pk_fma_f32 v[66:67], v[42:43], v[70:71], v[66:67]
	v_pk_fma_f32 v[64:65], v[44:45], v[60:61], v[64:65]
	v_pk_fma_f32 v[66:67], v[50:51], v[72:73], v[66:67]
	s_waitcnt lgkmcnt(0)
	v_lshlrev_b32_e32 v68, 16, v58
	v_and_b32_e32 v69, 0xffff0000, v58
	v_lshlrev_b32_e32 v58, 16, v59
	v_and_b32_e32 v59, 0xffff0000, v59
	v_pk_fma_f32 v[64:65], v[52:53], v[62:63], v[64:65]
	v_pk_fma_f32 v[66:67], v[38:39], v[68:69], v[66:67]
	v_pk_fma_f32 v[64:65], v[40:41], v[58:59], v[64:65]
	v_cvt_pk_bf16_f32 v66, v66, v67
	v_pk_fma_f32 v[70:71], v[34:35], v[70:71], v[46:47]
	v_cvt_pk_bf16_f32 v67, v64, v65
	ds_write_b64 v54, v[66:67] offset:9360
	ds_read_b64 v[64:65], v158 offset:13312
	v_pk_fma_f32 v[60:61], v[36:37], v[60:61], v[48:49]
	v_pk_fma_f32 v[70:71], v[42:43], v[72:73], v[70:71]
	v_pk_fma_f32 v[60:61], v[44:45], v[62:63], v[60:61]
	v_pk_fma_f32 v[70:71], v[50:51], v[68:69], v[70:71]
	s_waitcnt lgkmcnt(0)
	v_lshlrev_b32_e32 v66, 16, v64
	v_and_b32_e32 v67, 0xffff0000, v64
	v_lshlrev_b32_e32 v64, 16, v65
	v_and_b32_e32 v65, 0xffff0000, v65
	v_pk_fma_f32 v[60:61], v[52:53], v[58:59], v[60:61]
	v_pk_fma_f32 v[70:71], v[38:39], v[66:67], v[70:71]
	v_pk_fma_f32 v[60:61], v[40:41], v[64:65], v[60:61]
	v_cvt_pk_bf16_f32 v70, v70, v71
	v_pk_fma_f32 v[72:73], v[34:35], v[72:73], v[46:47]
	v_cvt_pk_bf16_f32 v71, v60, v61
	ds_write_b64 v54, v[70:71] offset:10400
	ds_read_b64 v[60:61], v158 offset:14336
	v_pk_fma_f32 v[62:63], v[36:37], v[62:63], v[48:49]
	v_pk_fma_f32 v[72:73], v[42:43], v[68:69], v[72:73]
	v_pk_fma_f32 v[62:63], v[44:45], v[58:59], v[62:63]
	v_pk_fma_f32 v[72:73], v[50:51], v[66:67], v[72:73]
	s_waitcnt lgkmcnt(0)
; __device__ __forceinline__ unsigned pk2(float lo, float hi) { unsigned r; asm("v_cvt_pk_bf16_f32 %0, %1, %2" : "=v"(r) : "v"(lo), "v"(hi)); return r; }
; template <int DIR>
; __device__ __forceinline__ void scan_dir(PP p, const bf16_t* xs, const ScanW& w, ScanW& wn, int ndir, int nct, bool do_next, int n, int ct, int l31, int hl, int id, int rowbase, bool latent, float (&hf)[2][16]) {
;     ...
;     bf16_t* yl = (bf16_t*)(p->ws + WS_YL) + (size_t)rowbase * 512; bf16_t* caf = (bf16_t*)(p->ws + WS_CAF) + (size_t)rowbase * 512; bf16_t* cab = (bf16_t*)(p->ws + WS_CAB) + (size_t)rowbase * 512;
; __device__ __forceinline__ void scan_mfma(PP p, unsigned char* shm, int wv) {
;     ...
; #pragma unroll
;             for (int t = 0; t < 16; ++t) {
;                 const f32x4 xp1 = ld4(16 * tq + t + 3);
;                 const f32x4 o = kb + k0 * xm2 + k1 * xm1 + k2 * x0 + k3 * xp1;
;                 u32x2 w; w.x = pk2(o[0], o[1]); w.y = pk2(o[2], o[3]);
;                 *(u32x2*)(xs + (16 * tq + t) * XS + c4) = w;
;                 xm2 = xm1; xm1 = x0; x0 = xp1;
;             }
;         }
;         __syncthreads();
	v_lshlrev_b32_e32 v70, 16, v60
	v_and_b32_e32 v71, 0xffff0000, v60
	v_lshlrev_b32_e32 v60, 16, v61
	v_and_b32_e32 v61, 0xffff0000, v61
	v_pk_fma_f32 v[62:63], v[52:53], v[64:65], v[62:63]
	v_pk_fma_f32 v[72:73], v[38:39], v[70:71], v[72:73]
	v_pk_fma_f32 v[62:63], v[40:41], v[60:61], v[62:63]
	v_cvt_pk_bf16_f32 v72, v72, v73
	v_pk_fma_f32 v[68:69], v[34:35], v[68:69], v[46:47]
	v_cvt_pk_bf16_f32 v73, v62, v63
	ds_write_b64 v54, v[72:73] offset:11440
	ds_read_b64 v[62:63], v158 offset:15360
	v_pk_fma_f32 v[58:59], v[36:37], v[58:59], v[48:49]
	v_pk_fma_f32 v[68:69], v[42:43], v[66:67], v[68:69]
	v_pk_fma_f32 v[58:59], v[44:45], v[64:65], v[58:59]
	v_pk_fma_f32 v[68:69], v[50:51], v[70:71], v[68:69]
	s_waitcnt lgkmcnt(0)
	v_lshlrev_b32_e32 v72, 16, v62
	v_and_b32_e32 v73, 0xffff0000, v62
	v_lshlrev_b32_e32 v62, 16, v63
	v_and_b32_e32 v63, 0xffff0000, v63
	v_pk_fma_f32 v[58:59], v[52:53], v[60:61], v[58:59]
	v_pk_fma_f32 v[68:69], v[38:39], v[72:73], v[68:69]
	v_pk_fma_f32 v[58:59], v[40:41], v[62:63], v[58:59]
	v_cvt_pk_bf16_f32 v68, v68, v69
	v_pk_fma_f32 v[66:67], v[34:35], v[66:67], v[46:47]
	v_cvt_pk_bf16_f32 v69, v58, v59
	ds_write_b64 v54, v[68:69] offset:12480
	ds_read_b64 v[58:59], v158 offset:16384
	v_pk_fma_f32 v[64:65], v[36:37], v[64:65], v[48:49]
	v_pk_fma_f32 v[66:67], v[42:43], v[70:71], v[66:67]
	v_pk_fma_f32 v[64:65], v[44:45], v[60:61], v[64:65]
	v_pk_fma_f32 v[66:67], v[50:51], v[72:73], v[66:67]
	s_waitcnt lgkmcnt(0)
	v_lshlrev_b32_e32 v68, 16, v58
	v_and_b32_e32 v69, 0xffff0000, v58
	v_lshlrev_b32_e32 v58, 16, v59
	v_and_b32_e32 v59, 0xffff0000, v59
	v_pk_fma_f32 v[64:65], v[52:53], v[62:63], v[64:65]
	v_pk_fma_f32 v[66:67], v[38:39], v[68:69], v[66:67]
	v_pk_fma_f32 v[64:65], v[40:41], v[58:59], v[64:65]
	v_cvt_pk_bf16_f32 v66, v66, v67
	v_pk_fma_f32 v[60:61], v[36:37], v[60:61], v[48:49]
	v_cvt_pk_bf16_f32 v67, v64, v65
	ds_write_b64 v54, v[66:67] offset:13520
	ds_read_b64 v[64:65], v158 offset:17408
	v_pk_fma_f32 v[70:71], v[34:35], v[70:71], v[46:47]
	v_pk_fma_f32 v[60:61], v[44:45], v[62:63], v[60:61]
	v_pk_fma_f32 v[70:71], v[42:43], v[72:73], v[70:71]
	v_pk_fma_f32 v[60:61], v[52:53], v[58:59], v[60:61]
	s_waitcnt lgkmcnt(0)
	v_lshlrev_b32_e32 v66, 16, v64
	v_and_b32_e32 v67, 0xffff0000, v64
	v_lshlrev_b32_e32 v64, 16, v65
	v_and_b32_e32 v65, 0xffff0000, v65
	v_pk_fma_f32 v[70:71], v[50:51], v[68:69], v[70:71]
	v_pk_fma_f32 v[60:61], v[40:41], v[64:65], v[60:61]
	v_pk_fma_f32 v[70:71], v[38:39], v[66:67], v[70:71]
	v_pk_fma_f32 v[36:37], v[36:37], v[62:63], v[48:49]
	v_cvt_pk_bf16_f32 v70, v70, v71
	v_cvt_pk_bf16_f32 v71, v60, v61
	v_or_b32_e32 v60, 15, v56
	ds_write_b64 v54, v[70:71] offset:14560
	v_lshl_add_u32 v54, v60, 10, v156
	ds_read_b64 v[54:55], v54 offset:3072
	v_pk_fma_f32 v[34:35], v[34:35], v[72:73], v[46:47]
	v_pk_fma_f32 v[36:37], v[44:45], v[58:59], v[36:37]
	v_pk_fma_f32 v[34:35], v[42:43], v[68:69], v[34:35]
	v_pk_fma_f32 v[36:37], v[52:53], v[64:65], v[36:37]
	s_waitcnt lgkmcnt(0)
	v_lshlrev_b32_e32 v56, 16, v54
	v_and_b32_e32 v57, 0xffff0000, v54
	v_lshlrev_b32_e32 v54, 16, v55
	v_and_b32_e32 v55, 0xffff0000, v55
	v_pk_fma_f32 v[34:35], v[50:51], v[66:67], v[34:35]
	v_pk_fma_f32 v[36:37], v[40:41], v[54:55], v[36:37]
	v_pk_fma_f32 v[34:35], v[38:39], v[56:57], v[34:35]
	s_nop 0
	v_cvt_pk_bf16_f32 v34, v34, v35
	v_cvt_pk_bf16_f32 v35, v36, v37
	v_mad_u64_u32 v[36:37], s[30:31], v60, s51, v[0:1]
	s_add_u32 s30, s52, s4
	s_addc_u32 s31, s53, s5
	s_ashr_i32 s35, s34, 31
	s_lshl_b64 s[34:35], s[34:35], 12
	s_add_u32 s34, s54, s34
	s_addc_u32 s35, s55, s35
	s_add_u32 s36, s57, s4
	s_addc_u32 s37, s58, s5
	s_add_u32 s38, s59, s4
	s_addc_u32 s39, s60, s5
	s_add_u32 s40, s34, 0x208000
	s_addc_u32 s41, s35, 0
	ds_write_b64 v36, v[34:35]
	s_waitcnt lgkmcnt(0)
	s_barrier
	s_branch .LBB0_371
